# adds HGRN state pass (phase 17): K/V transposed fragment reads issued a whole 16-key step ahead into a second register set, decay-row reads kept ten deep, instead of one LDS round trip per MFMA / per
# speedup vs baseline: 1.0122x; 1.0010x over previous
; #define LAS __attribute__((address_space(3)))
;     ...
;             if ((!FULL || j < 3) && !(probe & 1)) {
; #pragma unroll
;                 for (int st = 0; st < 4; ++st) { const bf16x8 vb = tr_pair(Vi, 16 * st + 8 * hi, 16 * st + 8 * hi + 4, w, lane);
; #pragma unroll
;                     for (int kb = 0; kb < 4; ++kb) S[kb] = __builtin_amdgcn_mfma_f32_32x32x16_bf16(tr_pair(K1, 16 * st + 8 * hi, 16 * st + 8 * hi + 4, kb, lane), vb, S[kb], 0, 0, 0); }
; #pragma unroll
;                 for (int kb = 0; kb < 4; ++kb)
; #pragma unroll
;                     for (int r4 = 0; r4 < 4; ++r4) { const f32x4 eb = *(const LAS f32x4*)(EBL + 32 * kb + 8 * r4 + 4 * hi);
; #pragma unroll
;                         for (int e = 0; e < 4; ++e) S[kb][4 * r4 + e] *= eb[e]; }
;             }
.LBB0_2313:
	s_waitcnt lgkmcnt(8)
	v_pk_mul_f32 v[64:65], v[64:65], v[92:93]
	v_pk_mul_f32 v[66:67], v[66:67], v[94:95]
	s_waitcnt lgkmcnt(0)
	s_barrier
	ds_read_b64_tr_b16 v[212:213], v168 offset:32768
	ds_read_b64_tr_b16 v[214:215], v169 offset:32768
	ds_read_b64_tr_b16 v[220:221], v170 offset:16384
	ds_read_b64_tr_b16 v[222:223], v171 offset:16384
	ds_read_b64_tr_b16 v[224:225], v172 offset:16384
	ds_read_b64_tr_b16 v[226:227], v173 offset:16384
	ds_read_b64_tr_b16 v[228:229], v174 offset:16384
	ds_read_b64_tr_b16 v[230:231], v175 offset:16384
	ds_read_b64_tr_b16 v[232:233], v176 offset:16384
	ds_read_b64_tr_b16 v[234:235], v177 offset:16384
	ds_read_b64_tr_b16 v[216:217], v168 offset:36864
	ds_read_b64_tr_b16 v[218:219], v178 offset:32768
	ds_read_b64_tr_b16 v[236:237], v170 offset:20480
	ds_read_b64_tr_b16 v[238:239], v179 offset:16384
	ds_read_b64_tr_b16 v[240:241], v172 offset:20480
	ds_read_b64_tr_b16 v[242:243], v180 offset:16384
	ds_read_b64_tr_b16 v[244:245], v174 offset:20480
	ds_read_b64_tr_b16 v[246:247], v181 offset:16384
	ds_read_b64_tr_b16 v[248:249], v176 offset:20480
	ds_read_b64_tr_b16 v[250:251], v182 offset:16384
	s_waitcnt lgkmcnt(10)
	v_mfma_f32_32x32x16_bf16 v[48:63], v[220:223], v[212:215], v[48:63]
	s_add_i32 s8, s8, 64
	v_mul_f32_e64 v68, v68, v96
	v_mul_f32_e64 v69, v69, v97
	v_pk_mul_f32 v[70:71], v[70:71], v[98:99]
	v_subrev_u32_e32 v200, 64, v200
	s_cmpk_eq_i32 s8, 0x100
	v_mfma_f32_32x32x16_bf16 v[32:47], v[224:227], v[212:215], v[32:47]
	v_mfma_f32_32x32x16_bf16 v[16:31], v[228:231], v[212:215], v[16:31]
	v_mfma_f32_32x32x16_bf16 v[0:15], v[232:235], v[212:215], v[0:15]
	ds_read_b64_tr_b16 v[212:213], v168 offset:40960
	ds_read_b64_tr_b16 v[214:215], v183 offset:32768
	ds_read_b64_tr_b16 v[220:221], v170 offset:24576
	ds_read_b64_tr_b16 v[222:223], v190 offset:16384
	ds_read_b64_tr_b16 v[224:225], v172 offset:24576
	ds_read_b64_tr_b16 v[226:227], v191 offset:16384
	ds_read_b64_tr_b16 v[228:229], v174 offset:24576
	ds_read_b64_tr_b16 v[230:231], v192 offset:16384
	ds_read_b64_tr_b16 v[232:233], v176 offset:24576
	ds_read_b64_tr_b16 v[234:235], v193 offset:16384
	s_waitcnt lgkmcnt(10)
	v_mfma_f32_32x32x16_bf16 v[48:63], v[236:239], v[216:219], v[48:63]
	v_mfma_f32_32x32x16_bf16 v[32:47], v[240:243], v[216:219], v[32:47]
	v_mfma_f32_32x32x16_bf16 v[16:31], v[244:247], v[216:219], v[16:31]
	v_mfma_f32_32x32x16_bf16 v[0:15], v[248:251], v[216:219], v[0:15]
	ds_read_b64_tr_b16 v[216:217], v168 offset:45056
	ds_read_b64_tr_b16 v[218:219], v194 offset:32768
	ds_read_b64_tr_b16 v[236:237], v170 offset:28672
	ds_read_b64_tr_b16 v[238:239], v195 offset:16384
	ds_read_b64_tr_b16 v[240:241], v172 offset:28672
	ds_read_b64_tr_b16 v[242:243], v196 offset:16384
	ds_read_b64_tr_b16 v[244:245], v174 offset:28672
	ds_read_b64_tr_b16 v[246:247], v197 offset:16384
	ds_read_b64_tr_b16 v[248:249], v176 offset:28672
	ds_read_b64_tr_b16 v[250:251], v198 offset:16384
	s_waitcnt lgkmcnt(10)
	v_mfma_f32_32x32x16_bf16 v[48:63], v[220:223], v[212:215], v[48:63]
	v_mfma_f32_32x32x16_bf16 v[32:47], v[224:227], v[212:215], v[32:47]
	v_mfma_f32_32x32x16_bf16 v[16:31], v[228:231], v[212:215], v[16:31]
	v_mfma_f32_32x32x16_bf16 v[0:15], v[232:235], v[212:215], v[0:15]
	s_waitcnt lgkmcnt(0)
	v_mfma_f32_32x32x16_bf16 v[48:63], v[236:239], v[216:219], v[48:63]
	v_mfma_f32_32x32x16_bf16 v[32:47], v[240:243], v[216:219], v[32:47]
	v_mfma_f32_32x32x16_bf16 v[16:31], v[244:247], v[216:219], v[16:31]
	v_mfma_f32_32x32x16_bf16 v[0:15], v[248:251], v[216:219], v[0:15]
	ds_read_b128 v[212:215], v199 offset:57344
	ds_read_b128 v[216:219], v199 offset:57376
	ds_read_b128 v[220:223], v199 offset:57408
	ds_read_b128 v[224:227], v199 offset:57440
	ds_read_b128 v[228:231], v199 offset:57472
	ds_read_b128 v[232:235], v199 offset:57504
	ds_read_b128 v[236:239], v199 offset:57536
	ds_read_b128 v[240:243], v199 offset:57568
	ds_read_b128 v[244:247], v199 offset:57600
	ds_read_b128 v[248:251], v199 offset:57632
	s_waitcnt lgkmcnt(9)
	v_mul_f32_e64 v48, v48, v212
	v_mul_f32_e64 v49, v49, v213
	v_pk_mul_f32 v[50:51], v[50:51], v[214:215]
	ds_read_b128 v[212:215], v199 offset:57664
	s_waitcnt lgkmcnt(9)
	v_pk_mul_f32 v[52:53], v[52:53], v[216:217]
	v_pk_mul_f32 v[54:55], v[54:55], v[218:219]
	ds_read_b128 v[216:219], v199 offset:57696
	s_waitcnt lgkmcnt(9)
	v_pk_mul_f32 v[56:57], v[56:57], v[220:221]
	v_pk_mul_f32 v[58:59], v[58:59], v[222:223]
	ds_read_b128 v[220:223], v199 offset:57728
	s_waitcnt lgkmcnt(9)
	v_pk_mul_f32 v[60:61], v[60:61], v[224:225]
	v_pk_mul_f32 v[62:63], v[62:63], v[226:227]
	ds_read_b128 v[224:227], v199 offset:57760
	s_waitcnt lgkmcnt(9)
	v_pk_mul_f32 v[32:33], v[32:33], v[228:229]
	v_pk_mul_f32 v[34:35], v[34:35], v[230:231]
	ds_read_b128 v[228:231], v199 offset:57792
	s_waitcnt lgkmcnt(9)
	v_pk_mul_f32 v[36:37], v[36:37], v[232:233]
	v_pk_mul_f32 v[38:39], v[38:39], v[234:235]
	ds_read_b128 v[232:235], v199 offset:57824
	s_waitcnt lgkmcnt(9)
	v_pk_mul_f32 v[40:41], v[40:41], v[236:237]
	v_pk_mul_f32 v[42:43], v[42:43], v[238:239]
	s_waitcnt lgkmcnt(8)
	v_pk_mul_f32 v[44:45], v[44:45], v[240:241]
	v_pk_mul_f32 v[46:47], v[46:47], v[242:243]
	s_waitcnt lgkmcnt(7)
	v_pk_mul_f32 v[16:17], v[16:17], v[244:245]
	v_pk_mul_f32 v[18:19], v[18:19], v[246:247]
	s_waitcnt lgkmcnt(6)
	v_pk_mul_f32 v[20:21], v[20:21], v[248:249]
	v_pk_mul_f32 v[22:23], v[22:23], v[250:251]
	s_waitcnt lgkmcnt(5)
	v_pk_mul_f32 v[24:25], v[24:25], v[212:213]
	v_pk_mul_f32 v[26:27], v[26:27], v[214:215]
	s_waitcnt lgkmcnt(4)
	v_pk_mul_f32 v[28:29], v[28:29], v[216:217]
	v_pk_mul_f32 v[30:31], v[30:31], v[218:219]
	s_waitcnt lgkmcnt(3)
	v_pk_mul_f32 v[0:1], v[0:1], v[220:221]
	v_pk_mul_f32 v[2:3], v[2:3], v[222:223]
	s_waitcnt lgkmcnt(2)
	v_pk_mul_f32 v[4:5], v[4:5], v[224:225]
	v_pk_mul_f32 v[6:7], v[6:7], v[226:227]
	s_waitcnt lgkmcnt(1)
	v_pk_mul_f32 v[8:9], v[8:9], v[228:229]
	v_pk_mul_f32 v[10:11], v[10:11], v[230:231]
	s_waitcnt lgkmcnt(0)
	s_barrier
	v_pk_mul_f32 v[12:13], v[12:13], v[232:233]
	v_pk_mul_f32 v[14:15], v[14:15], v[234:235]
	s_cbranch_scc1 .LBB0_2318
